# GU epilogue: hoist the 8 per-row-group rstd stat loads to epilogue start, counted vmcnt(7) instead of vmcnt(0) per row group
# speedup vs baseline: 1.0114x; 1.0114x over previous
.LBB0_410:
	v_lshl_add_u32 v140, s50, 8, v146
	v_ashrrev_i32_e32 v141, 31, v140
	v_lshl_add_u64 v[142:143], v[140:141], 2, s[46:47]
	global_load_dword v228, v[142:143], off sc1
	global_load_dword v229, v[142:143], off offset:64 sc1
	global_load_dword v230, v[142:143], off offset:128 sc1
	global_load_dword v231, v[142:143], off offset:192 sc1
	global_load_dword v232, v[142:143], off offset:512 sc1
	global_load_dword v233, v[142:143], off offset:576 sc1
	global_load_dword v234, v[142:143], off offset:640 sc1
	global_load_dword v235, v[142:143], off offset:704 sc1
	v_lshl_or_b32 v144, s52, 7, v148
	v_ashrrev_i32_e32 v145, 31, v144
	s_andn2_b64 vcc, exec, s[4:5]
	s_waitcnt vmcnt(7)
	v_fmamk_f32 v141, v228, 0x3a800000, v178
	v_rsq_f32_e32 v150, v141
	s_nop 0
	v_pk_mul_f32 v[126:127], v[126:127], v[150:151] op_sel_hi:[1,0]
	v_pk_mul_f32 v[118:119], v[118:119], v[150:151] op_sel_hi:[1,0]
	v_mul_f32_e32 v141, 0xbfb8aa3b, v126
	v_pk_mul_f32 v[118:119], v[126:127], v[118:119]
	v_mul_f32_e32 v126, 0xbfb8aa3b, v127
	v_exp_f32_e32 v126, v126
	v_pk_mul_f32 v[120:121], v[120:121], v[150:151] op_sel_hi:[1,0]
	v_pk_mul_f32 v[122:123], v[122:123], v[150:151] op_sel_hi:[1,0]
	v_pk_mul_f32 v[114:115], v[114:115], v[150:151] op_sel_hi:[1,0]
	v_add_f32_e32 v126, 1.0, v126
	v_rcp_f32_e32 v153, v126
	v_pk_mul_f32 v[126:127], v[128:129], v[150:151] op_sel_hi:[1,0]
	v_pk_mul_f32 v[114:115], v[122:123], v[114:115]
	v_mul_f32_e32 v128, 0xbfb8aa3b, v126
	v_pk_mul_f32 v[120:121], v[126:127], v[120:121]
	v_mul_f32_e32 v126, 0xbfb8aa3b, v127
	v_exp_f32_e32 v126, v126
	v_exp_f32_e32 v141, v141
	v_pk_mul_f32 v[116:117], v[116:117], v[150:151] op_sel_hi:[1,0]
	v_exp_f32_e32 v128, v128
	v_add_f32_e32 v126, 1.0, v126
	v_rcp_f32_e32 v129, v126
	v_mul_f32_e32 v126, 0xbfb8aa3b, v122
	v_mul_f32_e32 v122, 0xbfb8aa3b, v123
	v_exp_f32_e32 v126, v126
	v_exp_f32_e32 v122, v122
	v_add_f32_e32 v141, 1.0, v141
	v_rcp_f32_e32 v152, v141
	v_add_f32_e32 v126, 1.0, v126
	v_add_f32_e32 v122, 1.0, v122
	v_rcp_f32_e32 v126, v126
	v_rcp_f32_e32 v127, v122
	v_add_f32_e32 v128, 1.0, v128
	v_rcp_f32_e32 v128, v128
	v_pk_mul_f32 v[118:119], v[118:119], v[152:153]
	v_pk_mul_f32 v[122:123], v[114:115], v[126:127]
	v_pk_mul_f32 v[114:115], v[124:125], v[150:151] op_sel_hi:[1,0]
	v_pk_mul_f32 v[120:121], v[120:121], v[128:129]
	v_mul_f32_e32 v124, 0xbfb8aa3b, v114
	v_pk_mul_f32 v[116:117], v[114:115], v[116:117]
	v_mul_f32_e32 v114, 0xbfb8aa3b, v115
	v_exp_f32_e32 v124, v124
	v_exp_f32_e32 v114, v114
	v_cvt_pk_bf16_f32 v115, v120, v121
	v_lshlrev_b64 v[120:121], 1, v[144:145]
	v_add_f32_e32 v124, 1.0, v124
	v_add_f32_e32 v114, 1.0, v114
	v_rcp_f32_e32 v124, v124
	v_rcp_f32_e32 v125, v114
	v_cvt_pk_bf16_f32 v114, v118, v119
	v_mov_b64_e32 v[118:119], s[44:45]
	v_pk_mul_f32 v[124:125], v[116:117], v[124:125]
	v_cvt_pk_bf16_f32 v116, v122, v123
	v_mad_i64_i32 v[122:123], s[50:51], v140, s39, v[118:119]
	v_cvt_pk_bf16_f32 v117, v124, v125
	v_lshl_add_u64 v[122:123], v[122:123], 0, v[120:121]
	global_store_dwordx4 v[122:123], v[114:117], off
	s_nop 0
	s_nop 0
	v_or_b32_e32 v115, 16, v140
	s_waitcnt vmcnt(7)
	v_fmamk_f32 v114, v229, 0x3a800000, v178
	v_rsq_f32_e32 v114, v114
	s_nop 0
	v_pk_mul_f32 v[110:111], v[110:111], v[114:115] op_sel_hi:[1,0]
	v_pk_mul_f32 v[102:103], v[102:103], v[114:115] op_sel_hi:[1,0]
	v_mul_f32_e32 v116, 0xbfb8aa3b, v110
	v_pk_mul_f32 v[102:103], v[110:111], v[102:103]
	v_mul_f32_e32 v110, 0xbfb8aa3b, v111
	v_exp_f32_e32 v110, v110
	v_pk_mul_f32 v[104:105], v[104:105], v[114:115] op_sel_hi:[1,0]
	v_pk_mul_f32 v[106:107], v[106:107], v[114:115] op_sel_hi:[1,0]
	v_pk_mul_f32 v[98:99], v[98:99], v[114:115] op_sel_hi:[1,0]
	v_add_f32_e32 v110, 1.0, v110
	v_rcp_f32_e32 v117, v110
	v_pk_mul_f32 v[110:111], v[112:113], v[114:115] op_sel_hi:[1,0]
	v_pk_mul_f32 v[98:99], v[106:107], v[98:99]
	v_mul_f32_e32 v112, 0xbfb8aa3b, v110
	v_pk_mul_f32 v[104:105], v[110:111], v[104:105]
	v_mul_f32_e32 v110, 0xbfb8aa3b, v111
	v_exp_f32_e32 v110, v110
	v_pk_mul_f32 v[100:101], v[100:101], v[114:115] op_sel_hi:[1,0]
	v_exp_f32_e32 v116, v116
	v_exp_f32_e32 v112, v112
	v_add_f32_e32 v110, 1.0, v110
	v_rcp_f32_e32 v113, v110
	v_mul_f32_e32 v110, 0xbfb8aa3b, v106
	v_mul_f32_e32 v106, 0xbfb8aa3b, v107
	v_exp_f32_e32 v110, v110
	v_exp_f32_e32 v106, v106
	v_add_f32_e32 v116, 1.0, v116
	v_rcp_f32_e32 v116, v116
	v_add_f32_e32 v110, 1.0, v110
	v_add_f32_e32 v106, 1.0, v106
	v_rcp_f32_e32 v110, v110
	v_rcp_f32_e32 v111, v106
	v_add_f32_e32 v112, 1.0, v112
	v_rcp_f32_e32 v112, v112
	v_pk_mul_f32 v[102:103], v[102:103], v[116:117]
	v_pk_mul_f32 v[106:107], v[98:99], v[110:111]
	v_pk_mul_f32 v[98:99], v[108:109], v[114:115] op_sel_hi:[1,0]
	v_pk_mul_f32 v[104:105], v[104:105], v[112:113]
	v_mul_f32_e32 v108, 0xbfb8aa3b, v98
	v_pk_mul_f32 v[100:101], v[98:99], v[100:101]
	v_mul_f32_e32 v98, 0xbfb8aa3b, v99
	v_exp_f32_e32 v108, v108
	v_exp_f32_e32 v98, v98
	v_cvt_pk_bf16_f32 v99, v104, v105
	v_add_f32_e32 v108, 1.0, v108
	v_add_f32_e32 v98, 1.0, v98
	v_rcp_f32_e32 v108, v108
	v_rcp_f32_e32 v109, v98
	v_cvt_pk_bf16_f32 v98, v102, v103
	v_mad_i64_i32 v[102:103], s[50:51], v115, s39, v[118:119]
	v_pk_mul_f32 v[108:109], v[100:101], v[108:109]
	v_cvt_pk_bf16_f32 v100, v106, v107
	v_cvt_pk_bf16_f32 v101, v108, v109
	v_lshl_add_u64 v[102:103], v[102:103], 0, v[120:121]
	global_store_dwordx4 v[102:103], v[98:101], off
	s_nop 0
	s_nop 0
	v_or_b32_e32 v99, 32, v140
	s_waitcnt vmcnt(7)
	v_fmamk_f32 v98, v230, 0x3a800000, v178
	v_rsq_f32_e32 v98, v98
	s_nop 0
	v_pk_mul_f32 v[94:95], v[94:95], v[98:99] op_sel_hi:[1,0]
	v_pk_mul_f32 v[86:87], v[86:87], v[98:99] op_sel_hi:[1,0]
	v_mul_f32_e32 v100, 0xbfb8aa3b, v94
	v_pk_mul_f32 v[86:87], v[94:95], v[86:87]
	v_mul_f32_e32 v94, 0xbfb8aa3b, v95
	v_exp_f32_e32 v94, v94
	v_pk_mul_f32 v[88:89], v[88:89], v[98:99] op_sel_hi:[1,0]
	v_pk_mul_f32 v[90:91], v[90:91], v[98:99] op_sel_hi:[1,0]
	v_pk_mul_f32 v[82:83], v[82:83], v[98:99] op_sel_hi:[1,0]
	v_add_f32_e32 v94, 1.0, v94
	v_rcp_f32_e32 v101, v94
	v_pk_mul_f32 v[94:95], v[96:97], v[98:99] op_sel_hi:[1,0]
	v_pk_mul_f32 v[82:83], v[90:91], v[82:83]
	v_mul_f32_e32 v96, 0xbfb8aa3b, v94
	v_pk_mul_f32 v[88:89], v[94:95], v[88:89]
	v_mul_f32_e32 v94, 0xbfb8aa3b, v95
	v_exp_f32_e32 v94, v94
	v_pk_mul_f32 v[84:85], v[84:85], v[98:99] op_sel_hi:[1,0]
	v_exp_f32_e32 v100, v100
	v_exp_f32_e32 v96, v96
	v_add_f32_e32 v94, 1.0, v94
	v_rcp_f32_e32 v97, v94
	v_mul_f32_e32 v94, 0xbfb8aa3b, v90
	v_mul_f32_e32 v90, 0xbfb8aa3b, v91
	v_exp_f32_e32 v94, v94
	v_exp_f32_e32 v90, v90
	v_add_f32_e32 v100, 1.0, v100
	v_rcp_f32_e32 v100, v100
	v_add_f32_e32 v94, 1.0, v94
	v_add_f32_e32 v90, 1.0, v90
	v_rcp_f32_e32 v94, v94
	v_rcp_f32_e32 v95, v90
	v_add_f32_e32 v96, 1.0, v96
	v_rcp_f32_e32 v96, v96
	v_pk_mul_f32 v[86:87], v[86:87], v[100:101]
	v_pk_mul_f32 v[90:91], v[82:83], v[94:95]
	v_pk_mul_f32 v[82:83], v[92:93], v[98:99] op_sel_hi:[1,0]
	v_pk_mul_f32 v[88:89], v[88:89], v[96:97]
	v_mul_f32_e32 v92, 0xbfb8aa3b, v82
	v_pk_mul_f32 v[84:85], v[82:83], v[84:85]
	v_mul_f32_e32 v82, 0xbfb8aa3b, v83
	v_exp_f32_e32 v92, v92
	v_exp_f32_e32 v82, v82
	v_cvt_pk_bf16_f32 v83, v88, v89
	v_add_f32_e32 v92, 1.0, v92
	v_add_f32_e32 v82, 1.0, v82
	v_rcp_f32_e32 v92, v92
	v_rcp_f32_e32 v93, v82
	v_cvt_pk_bf16_f32 v82, v86, v87
	v_mad_i64_i32 v[86:87], s[50:51], v99, s39, v[118:119]
	v_pk_mul_f32 v[92:93], v[84:85], v[92:93]
	v_cvt_pk_bf16_f32 v84, v90, v91
	v_cvt_pk_bf16_f32 v85, v92, v93
	v_lshl_add_u64 v[86:87], v[86:87], 0, v[120:121]
	global_store_dwordx4 v[86:87], v[82:85], off
	s_nop 0
	s_nop 0
	v_or_b32_e32 v83, 48, v140
	s_waitcnt vmcnt(7)
	v_fmamk_f32 v82, v231, 0x3a800000, v178
	v_rsq_f32_e32 v82, v82
	s_nop 0
	v_pk_mul_f32 v[76:77], v[76:77], v[82:83] op_sel_hi:[1,0]
	v_pk_mul_f32 v[68:69], v[68:69], v[82:83] op_sel_hi:[1,0]
	v_mul_f32_e32 v84, 0xbfb8aa3b, v76
	v_pk_mul_f32 v[68:69], v[76:77], v[68:69]
	v_mul_f32_e32 v76, 0xbfb8aa3b, v77
	v_exp_f32_e32 v76, v76
	v_pk_mul_f32 v[70:71], v[70:71], v[82:83] op_sel_hi:[1,0]
	v_pk_mul_f32 v[72:73], v[72:73], v[82:83] op_sel_hi:[1,0]
	v_pk_mul_f32 v[64:65], v[64:65], v[82:83] op_sel_hi:[1,0]
	v_add_f32_e32 v76, 1.0, v76
	v_rcp_f32_e32 v85, v76
	v_pk_mul_f32 v[76:77], v[78:79], v[82:83] op_sel_hi:[1,0]
	v_pk_mul_f32 v[64:65], v[72:73], v[64:65]
	v_mul_f32_e32 v78, 0xbfb8aa3b, v76
	v_pk_mul_f32 v[70:71], v[76:77], v[70:71]
	v_mul_f32_e32 v76, 0xbfb8aa3b, v77
	v_exp_f32_e32 v76, v76
	v_pk_mul_f32 v[66:67], v[66:67], v[82:83] op_sel_hi:[1,0]
	v_exp_f32_e32 v84, v84
	v_exp_f32_e32 v78, v78
	v_add_f32_e32 v76, 1.0, v76
	v_rcp_f32_e32 v79, v76
	v_mul_f32_e32 v76, 0xbfb8aa3b, v72
	v_mul_f32_e32 v72, 0xbfb8aa3b, v73
	v_exp_f32_e32 v76, v76
	v_exp_f32_e32 v72, v72
	v_add_f32_e32 v84, 1.0, v84
	v_rcp_f32_e32 v84, v84
	v_add_f32_e32 v76, 1.0, v76
	v_add_f32_e32 v72, 1.0, v72
	v_rcp_f32_e32 v76, v76
	v_rcp_f32_e32 v77, v72
	v_add_f32_e32 v78, 1.0, v78
	v_rcp_f32_e32 v78, v78
	v_pk_mul_f32 v[68:69], v[68:69], v[84:85]
	v_pk_mul_f32 v[72:73], v[64:65], v[76:77]
	v_pk_mul_f32 v[64:65], v[74:75], v[82:83] op_sel_hi:[1,0]
	v_pk_mul_f32 v[70:71], v[70:71], v[78:79]
	v_mul_f32_e32 v74, 0xbfb8aa3b, v64
	v_pk_mul_f32 v[66:67], v[64:65], v[66:67]
	v_mul_f32_e32 v64, 0xbfb8aa3b, v65
	v_exp_f32_e32 v74, v74
	v_exp_f32_e32 v64, v64
	v_cvt_pk_bf16_f32 v65, v70, v71
	v_add_f32_e32 v74, 1.0, v74
	v_add_f32_e32 v64, 1.0, v64
	v_rcp_f32_e32 v74, v74
	v_rcp_f32_e32 v75, v64
	v_cvt_pk_bf16_f32 v64, v68, v69
	v_mad_i64_i32 v[68:69], s[50:51], v83, s39, v[118:119]
	v_pk_mul_f32 v[74:75], v[66:67], v[74:75]
	v_cvt_pk_bf16_f32 v66, v72, v73
	v_cvt_pk_bf16_f32 v67, v74, v75
	v_lshl_add_u64 v[68:69], v[68:69], 0, v[120:121]
	global_store_dwordx4 v[68:69], v[64:67], off
	s_nop 0
	s_nop 0
	v_add_u32_e32 v65, 0x80, v140
	s_waitcnt vmcnt(7)
	v_fmamk_f32 v64, v232, 0x3a800000, v178
	v_rsq_f32_e32 v64, v64
	s_nop 0
	v_pk_mul_f32 v[60:61], v[60:61], v[64:65] op_sel_hi:[1,0]
	v_pk_mul_f32 v[52:53], v[52:53], v[64:65] op_sel_hi:[1,0]
	v_mul_f32_e32 v66, 0xbfb8aa3b, v60
	v_pk_mul_f32 v[52:53], v[60:61], v[52:53]
	v_mul_f32_e32 v60, 0xbfb8aa3b, v61
	v_exp_f32_e32 v60, v60
	v_pk_mul_f32 v[54:55], v[54:55], v[64:65] op_sel_hi:[1,0]
	v_pk_mul_f32 v[56:57], v[56:57], v[64:65] op_sel_hi:[1,0]
	v_pk_mul_f32 v[48:49], v[48:49], v[64:65] op_sel_hi:[1,0]
	v_add_f32_e32 v60, 1.0, v60
	v_rcp_f32_e32 v67, v60
	v_pk_mul_f32 v[60:61], v[62:63], v[64:65] op_sel_hi:[1,0]
	v_pk_mul_f32 v[48:49], v[56:57], v[48:49]
	v_mul_f32_e32 v62, 0xbfb8aa3b, v60
	v_pk_mul_f32 v[54:55], v[60:61], v[54:55]
	v_mul_f32_e32 v60, 0xbfb8aa3b, v61
	v_exp_f32_e32 v60, v60
	v_pk_mul_f32 v[50:51], v[50:51], v[64:65] op_sel_hi:[1,0]
	v_exp_f32_e32 v66, v66
	v_exp_f32_e32 v62, v62
	v_add_f32_e32 v60, 1.0, v60
	v_rcp_f32_e32 v63, v60
	v_mul_f32_e32 v60, 0xbfb8aa3b, v56
	v_mul_f32_e32 v56, 0xbfb8aa3b, v57
	v_exp_f32_e32 v60, v60
	v_exp_f32_e32 v56, v56
	v_add_f32_e32 v66, 1.0, v66
	v_rcp_f32_e32 v66, v66
	v_add_f32_e32 v60, 1.0, v60
	v_add_f32_e32 v56, 1.0, v56
	v_rcp_f32_e32 v60, v60
	v_rcp_f32_e32 v61, v56
	v_add_f32_e32 v62, 1.0, v62
	v_rcp_f32_e32 v62, v62
	v_pk_mul_f32 v[52:53], v[52:53], v[66:67]
	v_pk_mul_f32 v[56:57], v[48:49], v[60:61]
	v_pk_mul_f32 v[48:49], v[58:59], v[64:65] op_sel_hi:[1,0]
	v_pk_mul_f32 v[54:55], v[54:55], v[62:63]
	v_mul_f32_e32 v58, 0xbfb8aa3b, v48
	v_pk_mul_f32 v[50:51], v[48:49], v[50:51]
	v_mul_f32_e32 v48, 0xbfb8aa3b, v49
	v_exp_f32_e32 v58, v58
	v_exp_f32_e32 v48, v48
	v_cvt_pk_bf16_f32 v49, v54, v55
	v_add_f32_e32 v58, 1.0, v58
	v_add_f32_e32 v48, 1.0, v48
	v_rcp_f32_e32 v58, v58
	v_rcp_f32_e32 v59, v48
	v_cvt_pk_bf16_f32 v48, v52, v53
	v_mad_i64_i32 v[52:53], s[50:51], v65, s39, v[118:119]
	v_pk_mul_f32 v[58:59], v[50:51], v[58:59]
	v_cvt_pk_bf16_f32 v50, v56, v57
	v_cvt_pk_bf16_f32 v51, v58, v59
	v_lshl_add_u64 v[52:53], v[52:53], 0, v[120:121]
	global_store_dwordx4 v[52:53], v[48:51], off
	s_nop 0
	s_nop 0
	v_add_u32_e32 v49, 0x90, v140
	s_waitcnt vmcnt(7)
	v_fmamk_f32 v48, v233, 0x3a800000, v178
	v_rsq_f32_e32 v48, v48
	s_nop 0
	v_pk_mul_f32 v[44:45], v[44:45], v[48:49] op_sel_hi:[1,0]
	v_pk_mul_f32 v[36:37], v[36:37], v[48:49] op_sel_hi:[1,0]
	v_mul_f32_e32 v50, 0xbfb8aa3b, v44
	v_pk_mul_f32 v[36:37], v[44:45], v[36:37]
	v_mul_f32_e32 v44, 0xbfb8aa3b, v45
	v_exp_f32_e32 v44, v44
	v_pk_mul_f32 v[38:39], v[38:39], v[48:49] op_sel_hi:[1,0]
	v_pk_mul_f32 v[40:41], v[40:41], v[48:49] op_sel_hi:[1,0]
	v_pk_mul_f32 v[32:33], v[32:33], v[48:49] op_sel_hi:[1,0]
	v_add_f32_e32 v44, 1.0, v44
	v_rcp_f32_e32 v51, v44
	v_pk_mul_f32 v[44:45], v[46:47], v[48:49] op_sel_hi:[1,0]
	v_pk_mul_f32 v[32:33], v[40:41], v[32:33]
	v_mul_f32_e32 v46, 0xbfb8aa3b, v44
	v_pk_mul_f32 v[38:39], v[44:45], v[38:39]
	v_mul_f32_e32 v44, 0xbfb8aa3b, v45
	v_exp_f32_e32 v44, v44
	v_pk_mul_f32 v[34:35], v[34:35], v[48:49] op_sel_hi:[1,0]
	v_exp_f32_e32 v50, v50
	v_exp_f32_e32 v46, v46
	v_add_f32_e32 v44, 1.0, v44
	v_rcp_f32_e32 v47, v44
	v_mul_f32_e32 v44, 0xbfb8aa3b, v40
	v_mul_f32_e32 v40, 0xbfb8aa3b, v41
	v_exp_f32_e32 v44, v44
	v_exp_f32_e32 v40, v40
	v_add_f32_e32 v50, 1.0, v50
	v_rcp_f32_e32 v50, v50
	v_add_f32_e32 v44, 1.0, v44
	v_add_f32_e32 v40, 1.0, v40
	v_rcp_f32_e32 v44, v44
	v_rcp_f32_e32 v45, v40
	v_add_f32_e32 v46, 1.0, v46
	v_rcp_f32_e32 v46, v46
	v_pk_mul_f32 v[36:37], v[36:37], v[50:51]
	v_pk_mul_f32 v[40:41], v[32:33], v[44:45]
	v_pk_mul_f32 v[32:33], v[42:43], v[48:49] op_sel_hi:[1,0]
	v_pk_mul_f32 v[38:39], v[38:39], v[46:47]
	v_mul_f32_e32 v42, 0xbfb8aa3b, v32
	v_pk_mul_f32 v[34:35], v[32:33], v[34:35]
	v_mul_f32_e32 v32, 0xbfb8aa3b, v33
	v_exp_f32_e32 v42, v42
	v_exp_f32_e32 v32, v32
	v_cvt_pk_bf16_f32 v33, v38, v39
	v_add_f32_e32 v42, 1.0, v42
	v_add_f32_e32 v32, 1.0, v32
	v_rcp_f32_e32 v42, v42
	v_rcp_f32_e32 v43, v32
	v_cvt_pk_bf16_f32 v32, v36, v37
	v_mad_i64_i32 v[36:37], s[50:51], v49, s39, v[118:119]
	v_pk_mul_f32 v[42:43], v[34:35], v[42:43]
	v_cvt_pk_bf16_f32 v34, v40, v41
	v_cvt_pk_bf16_f32 v35, v42, v43
	v_lshl_add_u64 v[36:37], v[36:37], 0, v[120:121]
	global_store_dwordx4 v[36:37], v[32:35], off
	s_nop 0
	s_nop 0
	v_add_u32_e32 v33, 0xa0, v140
	s_waitcnt vmcnt(7)
	v_fmamk_f32 v32, v234, 0x3a800000, v178
	v_rsq_f32_e32 v32, v32
	s_nop 0
	v_pk_mul_f32 v[28:29], v[28:29], v[32:33] op_sel_hi:[1,0]
	v_pk_mul_f32 v[20:21], v[20:21], v[32:33] op_sel_hi:[1,0]
	v_mul_f32_e32 v34, 0xbfb8aa3b, v28
	v_pk_mul_f32 v[20:21], v[28:29], v[20:21]
	v_mul_f32_e32 v28, 0xbfb8aa3b, v29
	v_exp_f32_e32 v28, v28
	v_pk_mul_f32 v[22:23], v[22:23], v[32:33] op_sel_hi:[1,0]
	v_pk_mul_f32 v[24:25], v[24:25], v[32:33] op_sel_hi:[1,0]
	v_pk_mul_f32 v[16:17], v[16:17], v[32:33] op_sel_hi:[1,0]
	v_add_f32_e32 v28, 1.0, v28
	v_rcp_f32_e32 v35, v28
	v_pk_mul_f32 v[28:29], v[30:31], v[32:33] op_sel_hi:[1,0]
	v_pk_mul_f32 v[16:17], v[24:25], v[16:17]
	v_mul_f32_e32 v30, 0xbfb8aa3b, v28
	v_pk_mul_f32 v[22:23], v[28:29], v[22:23]
	v_mul_f32_e32 v28, 0xbfb8aa3b, v29
	v_exp_f32_e32 v28, v28
	v_pk_mul_f32 v[18:19], v[18:19], v[32:33] op_sel_hi:[1,0]
	v_exp_f32_e32 v34, v34
	v_exp_f32_e32 v30, v30
	v_add_f32_e32 v28, 1.0, v28
	v_rcp_f32_e32 v31, v28
	v_mul_f32_e32 v28, 0xbfb8aa3b, v24
	v_mul_f32_e32 v24, 0xbfb8aa3b, v25
	v_exp_f32_e32 v28, v28
	v_exp_f32_e32 v24, v24
	v_add_f32_e32 v34, 1.0, v34
	v_rcp_f32_e32 v34, v34
	v_add_f32_e32 v28, 1.0, v28
	v_add_f32_e32 v24, 1.0, v24
	v_rcp_f32_e32 v28, v28
	v_rcp_f32_e32 v29, v24
	v_add_f32_e32 v30, 1.0, v30
	v_rcp_f32_e32 v30, v30
	v_pk_mul_f32 v[20:21], v[20:21], v[34:35]
	v_pk_mul_f32 v[24:25], v[16:17], v[28:29]
	v_pk_mul_f32 v[16:17], v[26:27], v[32:33] op_sel_hi:[1,0]
	v_pk_mul_f32 v[22:23], v[22:23], v[30:31]
	v_mul_f32_e32 v26, 0xbfb8aa3b, v16
	v_pk_mul_f32 v[18:19], v[16:17], v[18:19]
	v_mul_f32_e32 v16, 0xbfb8aa3b, v17
	v_exp_f32_e32 v26, v26
	v_exp_f32_e32 v16, v16
	v_cvt_pk_bf16_f32 v17, v22, v23
	v_add_f32_e32 v26, 1.0, v26
	v_add_f32_e32 v16, 1.0, v16
	v_rcp_f32_e32 v26, v26
	v_rcp_f32_e32 v27, v16
	v_cvt_pk_bf16_f32 v16, v20, v21
	v_mad_i64_i32 v[20:21], s[50:51], v33, s39, v[118:119]
	v_pk_mul_f32 v[26:27], v[18:19], v[26:27]
	v_cvt_pk_bf16_f32 v18, v24, v25
	v_cvt_pk_bf16_f32 v19, v26, v27
	v_lshl_add_u64 v[20:21], v[20:21], 0, v[120:121]
	global_store_dwordx4 v[20:21], v[16:19], off
	s_nop 0
	s_nop 0
	v_add_u32_e32 v17, 0xb0, v140
	s_waitcnt vmcnt(7)
	v_fmamk_f32 v16, v235, 0x3a800000, v178
	v_rsq_f32_e32 v16, v16
	s_nop 0
	v_pk_mul_f32 v[12:13], v[12:13], v[16:17] op_sel_hi:[1,0]
	v_pk_mul_f32 v[4:5], v[4:5], v[16:17] op_sel_hi:[1,0]
	v_mul_f32_e32 v18, 0xbfb8aa3b, v12
	v_pk_mul_f32 v[4:5], v[12:13], v[4:5]
	v_mul_f32_e32 v12, 0xbfb8aa3b, v13
	v_exp_f32_e32 v12, v12
	v_pk_mul_f32 v[6:7], v[6:7], v[16:17] op_sel_hi:[1,0]
	v_pk_mul_f32 v[8:9], v[8:9], v[16:17] op_sel_hi:[1,0]
	v_pk_mul_f32 v[0:1], v[0:1], v[16:17] op_sel_hi:[1,0]
	v_add_f32_e32 v12, 1.0, v12
	v_rcp_f32_e32 v19, v12
	v_pk_mul_f32 v[12:13], v[14:15], v[16:17] op_sel_hi:[1,0]
	v_pk_mul_f32 v[0:1], v[8:9], v[0:1]
	v_mul_f32_e32 v14, 0xbfb8aa3b, v12
	v_pk_mul_f32 v[6:7], v[12:13], v[6:7]
	v_mul_f32_e32 v12, 0xbfb8aa3b, v13
	v_exp_f32_e32 v12, v12
	v_pk_mul_f32 v[2:3], v[2:3], v[16:17] op_sel_hi:[1,0]
	v_exp_f32_e32 v18, v18
	v_exp_f32_e32 v14, v14
	v_add_f32_e32 v12, 1.0, v12
	v_rcp_f32_e32 v15, v12
	v_mul_f32_e32 v12, 0xbfb8aa3b, v8
	v_mul_f32_e32 v8, 0xbfb8aa3b, v9
	v_exp_f32_e32 v12, v12
	v_exp_f32_e32 v8, v8
	v_add_f32_e32 v18, 1.0, v18
	v_rcp_f32_e32 v18, v18
	v_add_f32_e32 v12, 1.0, v12
	v_add_f32_e32 v8, 1.0, v8
	v_rcp_f32_e32 v12, v12
	v_rcp_f32_e32 v13, v8
	v_add_f32_e32 v14, 1.0, v14
	v_rcp_f32_e32 v14, v14
	v_pk_mul_f32 v[4:5], v[4:5], v[18:19]
	v_pk_mul_f32 v[8:9], v[0:1], v[12:13]
	v_pk_mul_f32 v[0:1], v[10:11], v[16:17] op_sel_hi:[1,0]
	v_pk_mul_f32 v[6:7], v[6:7], v[14:15]
	v_mul_f32_e32 v10, 0xbfb8aa3b, v0
	v_pk_mul_f32 v[2:3], v[0:1], v[2:3]
	v_mul_f32_e32 v0, 0xbfb8aa3b, v1
	v_exp_f32_e32 v10, v10
	v_exp_f32_e32 v0, v0
	v_cvt_pk_bf16_f32 v1, v6, v7
	v_add_f32_e32 v10, 1.0, v10
	v_add_f32_e32 v0, 1.0, v0
	v_rcp_f32_e32 v10, v10
	v_rcp_f32_e32 v11, v0
	v_cvt_pk_bf16_f32 v0, v4, v5
	v_mad_i64_i32 v[4:5], s[50:51], v17, s39, v[118:119]
	v_pk_mul_f32 v[10:11], v[2:3], v[10:11]
	v_cvt_pk_bf16_f32 v2, v8, v9
	v_cvt_pk_bf16_f32 v3, v10, v11
	v_lshl_add_u64 v[4:5], v[4:5], 0, v[120:121]
	s_mov_b64 s[50:51], -1
	global_store_dwordx4 v[4:5], v[0:3], off
	s_cbranch_vccnz .LBB0_392
	s_andn2_b64 vcc, exec, s[42:43]
	s_cbranch_vccnz .LBB0_391
	s_barrier
	s_branch .LBB0_391
